# GEMM k-steps: two-level fragment wait (first 8 LDS reads, 16 MFMAs, then the rest) instead of one full drain
# speedup vs baseline: 1.0488x; 1.0030x over previous
; template <int MODE>
; __device__ void phase_gemm(const Params& p, int l, char* smem, int mtiles, int* s_item, int wv) {
;     ...
;     auto stage = [&](int kt, int buf) {
;       char* SA = smem + buf * 24576;
;       char* SB = SA + 16384;
;       const char* ab = (const char*)A + ((size_t)brow * 1024 + kt * 32) * 2;
;       const char* bb = (const char*)Bt + ((size_t)bcol * 1024 + kt * 32) * 2;
; #pragma unroll
;       for (int i = 0; i < 4; ++i) glds16(ab + (size_t)i * (64 * 2048) + voff, SA + tid * 16 + i * 4096);
; #pragma unroll
;       for (int i = 0; i < 2; ++i) glds16(bb + (size_t)i * (64 * 2048) + voff, SB + tid * 16 + i * 4096);
;     };
;     __syncthreads();
;     stage(0, 0);
;     stage(1, 1);
;     int buf = 0;
;     for (int kt = 0; kt < 32; ++kt) {
;       if (kt < 31) asm volatile("s_waitcnt vmcnt(6)" ::: "memory");
;       else asm volatile("s_waitcnt vmcnt(0)" ::: "memory");
;       __builtin_amdgcn_s_barrier();
;       int nb = buf + 2; nb = nb >= 3 ? nb - 3 : nb;
;       if (kt + 2 < 32) stage(kt + 2, nb);
;       const char* SA = smem + buf * 24576;
;       const char* SB = SA + 16384;
;       bf16x8 af[8], bfr[4];
; #pragma unroll
;       for (int n = 0; n < 4; ++n) bfr[n] = *(const bf16x8*)(SB + (wc * 64 + n * 16 + fr) * 64 + (fq ^ (fr >> 2)) * 16);
; #pragma unroll
;       for (int m = 0; m < 8; ++m) af[m] = *(const bf16x8*)(SA + (wr * 128 + m * 16 + fr) * 64 + (fq ^ (fr >> 2)) * 16);
;       __builtin_amdgcn_sched_barrier(0);
;       __builtin_amdgcn_s_setprio(1);
; #pragma unroll
;       for (int m = 0; m < 8; ++m)
; #pragma unroll
;         for (int n = 0; n < 4; ++n) acc[m][n] = mfma16(bfr[n], af[m], acc[m][n]);
;       __builtin_amdgcn_s_setprio(0);
;       buf = buf + 1 == 3 ? 0 : buf + 1;
;     }
.LBB0_180:
	s_cmp_gt_i32 s1, 0
	s_cselect_b32 s39, -1, 2
	s_add_i32 s39, s39, s1
	s_mulk_i32 s39, 0x6000
	v_add_u32_e32 v0, s39, v147
	v_lshl_add_u64 v[142:143], v[140:141], 0, s[2:3]
	v_readfirstlane_b32 s39, v0
	v_add_u32_e32 v152, 0x1000, v0
	v_lshl_add_u64 v[144:145], v[142:143], 0, s[52:53]
	s_mov_b32 m0, s39
	v_readfirstlane_b32 s39, v152
	v_add_u32_e32 v152, 0x2000, v0
	s_waitcnt vmcnt(6)
	s_barrier
	global_load_lds_dwordx4 v[144:145], off
	v_lshl_add_u64 v[144:145], v[142:143], 0, s[54:55]
	s_mov_b32 m0, s39
	v_readfirstlane_b32 s39, v152
	global_load_lds_dwordx4 v[144:145], off
	v_lshl_add_u64 v[144:145], v[142:143], 0, s[56:57]
	s_mov_b32 m0, s39
	v_lshl_add_u64 v[142:143], v[142:143], 0, s[58:59]
	global_load_lds_dwordx4 v[144:145], off
	v_add_u32_e32 v144, 0x3000, v0
	v_add_u32_e32 v152, 0x4000, v0
	v_readfirstlane_b32 s39, v144
	s_mov_b32 m0, s39
	s_mov_b64 s[40:41], 0x80
	global_load_lds_dwordx4 v[142:143], off
	v_lshl_add_u64 v[142:143], v[138:139], 0, s[2:3]
	v_readfirstlane_b32 s39, v152
	v_add_u32_e32 v0, 0x5000, v0
	v_lshl_add_u64 v[144:145], v[142:143], 0, s[40:41]
	s_mov_b32 m0, s39
	s_mov_b64 s[40:41], 0x20080
	v_readfirstlane_b32 s39, v0
	global_load_lds_dwordx4 v[144:145], off
	v_lshl_add_u64 v[142:143], v[142:143], 0, s[40:41]
	s_mov_b32 m0, s39
	s_mul_i32 s39, s1, 0x6000
	global_load_lds_dwordx4 v[142:143], off
	v_add_u32_e32 v0, s39, v151
	v_add_u32_e32 v160, v0, v148
	v_add_u32_e32 v176, v0, v149
	ds_read_b128 v[142:145], v160 offset:16384
	ds_read_b128 v[152:155], v160 offset:17408
	ds_read_b128 v[156:159], v160 offset:18432
	ds_read_b128 v[160:163], v160 offset:19456
	ds_read_b128 v[164:167], v176
	ds_read_b128 v[168:171], v176 offset:1024
	ds_read_b128 v[172:175], v176 offset:2048
	ds_read_b128 v[182:185], v176 offset:3072
	ds_read_b128 v[186:189], v176 offset:4096
	ds_read_b128 v[190:193], v176 offset:5120
	v_add_u32_e32 v0, v0, v150
	ds_read_b128 v[194:197], v176 offset:6144
	ds_read_b128 v[198:201], v0
	s_setprio 1
	s_waitcnt lgkmcnt(4)
	v_mfma_f32_16x16x32_bf16 v[126:129], v[142:145], v[164:167], v[126:129]
	v_mfma_f32_16x16x32_bf16 v[122:125], v[152:155], v[164:167], v[122:125]
	v_mfma_f32_16x16x32_bf16 v[118:121], v[156:159], v[164:167], v[118:121]
	v_mfma_f32_16x16x32_bf16 v[114:117], v[160:163], v[164:167], v[114:117]
	v_mfma_f32_16x16x32_bf16 v[110:113], v[142:145], v[168:171], v[110:113]
	v_mfma_f32_16x16x32_bf16 v[106:109], v[152:155], v[168:171], v[106:109]
	v_mfma_f32_16x16x32_bf16 v[102:105], v[156:159], v[168:171], v[102:105]
	v_mfma_f32_16x16x32_bf16 v[98:101], v[160:163], v[168:171], v[98:101]
	v_mfma_f32_16x16x32_bf16 v[94:97], v[142:145], v[172:175], v[94:97]
	v_mfma_f32_16x16x32_bf16 v[90:93], v[152:155], v[172:175], v[90:93]
	v_mfma_f32_16x16x32_bf16 v[86:89], v[156:159], v[172:175], v[86:89]
	v_mfma_f32_16x16x32_bf16 v[82:85], v[160:163], v[172:175], v[82:85]
	v_mfma_f32_16x16x32_bf16 v[78:81], v[142:145], v[182:185], v[78:81]
	v_mfma_f32_16x16x32_bf16 v[74:77], v[152:155], v[182:185], v[74:77]
	v_mfma_f32_16x16x32_bf16 v[70:73], v[156:159], v[182:185], v[70:73]
	v_mfma_f32_16x16x32_bf16 v[66:69], v[160:163], v[182:185], v[66:69]
	s_waitcnt lgkmcnt(0)
	v_mfma_f32_16x16x32_bf16 v[62:65], v[142:145], v[186:189], v[62:65]
	v_mfma_f32_16x16x32_bf16 v[58:61], v[152:155], v[186:189], v[58:61]
	v_mfma_f32_16x16x32_bf16 v[54:57], v[156:159], v[186:189], v[54:57]
	v_mfma_f32_16x16x32_bf16 v[50:53], v[160:163], v[186:189], v[50:53]
	v_mfma_f32_16x16x32_bf16 v[46:49], v[142:145], v[190:193], v[46:49]
	v_mfma_f32_16x16x32_bf16 v[42:45], v[152:155], v[190:193], v[42:45]
	v_mfma_f32_16x16x32_bf16 v[38:41], v[156:159], v[190:193], v[38:41]
	v_mfma_f32_16x16x32_bf16 v[34:37], v[160:163], v[190:193], v[34:37]
	v_mfma_f32_16x16x32_bf16 v[30:33], v[142:145], v[194:197], v[30:33]
	v_mfma_f32_16x16x32_bf16 v[26:29], v[152:155], v[194:197], v[26:29]
	v_mfma_f32_16x16x32_bf16 v[22:25], v[156:159], v[194:197], v[22:25]
	v_mfma_f32_16x16x32_bf16 v[18:21], v[160:163], v[194:197], v[18:21]
	v_mfma_f32_16x16x32_bf16 v[14:17], v[142:145], v[198:201], v[14:17]
	v_mfma_f32_16x16x32_bf16 v[10:13], v[152:155], v[198:201], v[10:13]
	v_mfma_f32_16x16x32_bf16 v[6:9], v[156:159], v[198:201], v[6:9]
	v_mfma_f32_16x16x32_bf16 v[2:5], v[160:163], v[198:201], v[2:5]
	s_setprio 0
	s_add_i32 s1, s1, 1
	s_cmp_lg_u32 s1, 3
	s_cselect_b32 s1, s1, 0
	s_add_u32 s2, s2, 64
	s_addc_u32 s3, s3, 0
	s_cmpk_eq_i32 s2, 0x780
	s_cbranch_scc0 .LBB0_180
	s_mulk_i32 s1, 0x6000
	v_add_u32_e32 v0, s1, v151
	v_add_u32_e32 v156, v0, v148
	v_add_u32_e32 v176, v0, v149
	s_waitcnt vmcnt(6)
	s_barrier
; template <int MODE>
; __device__ void phase_gemm(const Params& p, int l, char* smem, int mtiles, int* s_item, int wv) {
;     ...
;     for (int kt = 0; kt < 32; ++kt) {
;       if (kt < 31) asm volatile("s_waitcnt vmcnt(6)" ::: "memory");
;       else asm volatile("s_waitcnt vmcnt(0)" ::: "memory");
;       __builtin_amdgcn_s_barrier();
;       int nb = buf + 2; nb = nb >= 3 ? nb - 3 : nb;
;       if (kt + 2 < 32) stage(kt + 2, nb);
;       const char* SA = smem + buf * 24576;
;       const char* SB = SA + 16384;
;       bf16x8 af[8], bfr[4];
; #pragma unroll
;       for (int n = 0; n < 4; ++n) bfr[n] = *(const bf16x8*)(SB + (wc * 64 + n * 16 + fr) * 64 + (fq ^ (fr >> 2)) * 16);
; #pragma unroll
;       for (int m = 0; m < 8; ++m) af[m] = *(const bf16x8*)(SA + (wr * 128 + m * 16 + fr) * 64 + (fq ^ (fr >> 2)) * 16);
;       __builtin_amdgcn_sched_barrier(0);
;       __builtin_amdgcn_s_setprio(1);
; #pragma unroll
;       for (int m = 0; m < 8; ++m)
; #pragma unroll
;         for (int n = 0; n < 4; ++n) acc[m][n] = mfma16(bfr[n], af[m], acc[m][n]);
;       __builtin_amdgcn_s_setprio(0);
;       buf = buf + 1 == 3 ? 0 : buf + 1;
;     }
	ds_read_b128 v[138:141], v156 offset:16384
	ds_read_b128 v[142:145], v156 offset:17408
	ds_read_b128 v[152:155], v156 offset:18432
	ds_read_b128 v[156:159], v156 offset:19456
	ds_read_b128 v[160:163], v176
	ds_read_b128 v[164:167], v176 offset:1024
	ds_read_b128 v[168:171], v176 offset:2048
	ds_read_b128 v[172:175], v176 offset:3072
	ds_read_b128 v[182:185], v176 offset:4096
	ds_read_b128 v[186:189], v176 offset:5120
	v_add_u32_e32 v0, v0, v150
	ds_read_b128 v[190:193], v176 offset:6144
	ds_read_b128 v[194:197], v0
	s_setprio 1
	s_waitcnt lgkmcnt(0)
	v_mfma_f32_16x16x32_bf16 v[126:129], v[138:141], v[160:163], v[126:129]
	v_mfma_f32_16x16x32_bf16 v[122:125], v[142:145], v[160:163], v[122:125]
	v_mfma_f32_16x16x32_bf16 v[110:113], v[138:141], v[164:167], v[110:113]
	v_mfma_f32_16x16x32_bf16 v[106:109], v[142:145], v[164:167], v[106:109]
	v_mfma_f32_16x16x32_bf16 v[94:97], v[138:141], v[168:171], v[94:97]
	v_mfma_f32_16x16x32_bf16 v[90:93], v[142:145], v[168:171], v[90:93]
	v_mfma_f32_16x16x32_bf16 v[78:81], v[138:141], v[172:175], v[78:81]
	v_mfma_f32_16x16x32_bf16 v[74:77], v[142:145], v[172:175], v[74:77]
	v_mfma_f32_16x16x32_bf16 v[62:65], v[138:141], v[182:185], v[62:65]
	v_mfma_f32_16x16x32_bf16 v[58:61], v[142:145], v[182:185], v[58:61]
	v_mfma_f32_16x16x32_bf16 v[46:49], v[138:141], v[186:189], v[46:49]
	v_mfma_f32_16x16x32_bf16 v[42:45], v[142:145], v[186:189], v[42:45]
	v_mfma_f32_16x16x32_bf16 v[30:33], v[138:141], v[190:193], v[30:33]
	v_mfma_f32_16x16x32_bf16 v[26:29], v[142:145], v[190:193], v[26:29]
	v_mfma_f32_16x16x32_bf16 v[14:17], v[138:141], v[194:197], v[14:17]
	v_mfma_f32_16x16x32_bf16 v[10:13], v[142:145], v[194:197], v[10:13]
	v_mfma_f32_16x16x32_bf16 v[138:141], v[152:155], v[194:197], v[6:9]
	v_mfma_f32_16x16x32_bf16 v[142:145], v[156:159], v[194:197], v[2:5]
	v_mfma_f32_16x16x32_bf16 v[198:201], v[152:155], v[160:163], v[118:121]
	v_mfma_f32_16x16x32_bf16 v[160:163], v[156:159], v[160:163], v[114:117]
	v_mfma_f32_16x16x32_bf16 v[202:205], v[152:155], v[164:167], v[102:105]
	v_mfma_f32_16x16x32_bf16 v[164:167], v[156:159], v[164:167], v[98:101]
	v_mfma_f32_16x16x32_bf16 v[206:209], v[152:155], v[168:171], v[86:89]
	v_mfma_f32_16x16x32_bf16 v[168:171], v[156:159], v[168:171], v[82:85]
	v_mfma_f32_16x16x32_bf16 v[210:213], v[152:155], v[172:175], v[70:73]
	v_mfma_f32_16x16x32_bf16 v[172:175], v[156:159], v[172:175], v[66:69]
	v_mfma_f32_16x16x32_bf16 v[214:217], v[152:155], v[182:185], v[54:57]
	v_mfma_f32_16x16x32_bf16 v[182:185], v[156:159], v[182:185], v[50:53]
	v_mfma_f32_16x16x32_bf16 v[218:221], v[152:155], v[186:189], v[38:41]
	v_mfma_f32_16x16x32_bf16 v[186:189], v[156:159], v[186:189], v[34:37]
	v_mfma_f32_16x16x32_bf16 v[222:225], v[152:155], v[190:193], v[22:25]
	v_mfma_f32_16x16x32_bf16 v[190:193], v[156:159], v[190:193], v[18:21]
	s_setprio 0
	v_add_u32_e32 v0, v151, v148
	s_waitcnt vmcnt(0)
	s_barrier
; template <int MODE>
; __device__ void phase_gemm(const Params& p, int l, char* smem, int mtiles, int* s_item, int wv) {
;     ...
;       const char* SA = smem + buf * 24576;
;       const char* SB = SA + 16384;
;       bf16x8 af[8], bfr[4];
; #pragma unroll
;       for (int n = 0; n < 4; ++n) bfr[n] = *(const bf16x8*)(SB + (wc * 64 + n * 16 + fr) * 64 + (fq ^ (fr >> 2)) * 16);
; #pragma unroll
;       for (int m = 0; m < 8; ++m) af[m] = *(const bf16x8*)(SA + (wr * 128 + m * 16 + fr) * 64 + (fq ^ (fr >> 2)) * 16);
;       __builtin_amdgcn_sched_barrier(0);
;       __builtin_amdgcn_s_setprio(1);
; #pragma unroll
;       for (int m = 0; m < 8; ++m)
; #pragma unroll
;         for (int n = 0; n < 4; ++n) acc[m][n] = mfma16(bfr[n], af[m], acc[m][n]);
;       __builtin_amdgcn_s_setprio(0);
;       buf = buf + 1 == 3 ? 0 : buf + 1;
;     }
;     int tid_e = tid;
;     asm volatile("" : "+v"(tid_e));
;     const int fr = tid_e & 15, fq = (tid_e >> 4) & 3, wr = tid_e >> 7, wc = (tid_e >> 6) & 1;
;     const int col0 = bcol + wc * 64;
;     if (MODE == 1) {
;       u16* P = (u16*)(p.ws + OFF_P);
;       float* SC = (float*)(p.ws + OFF_SC);
;       const float2* rope = (const float2*)(p.ws + OFF_ROPE);
;       if (col0 >= 3328) {
;         if (col0 == 3328) {
; #pragma unroll
;           for (int m = 0; m < 8; ++m) {
;             int row = brow + wr * 128 + m * 16 + fr;
; #pragma unroll
;             for (int n = 0; n < 2; ++n)
;               *(float4*)(SC + (size_t)row * 32 + n * 16 + fq * 4) =
;                   make_float4(acc[m][n][0], acc[m][n][1], acc[m][n][2], acc[m][n][3]);
;           }
;         }
;       } else {
;         const bool ropecols = col0 >= C_QC && col0 < C_VC;
;         const bool isq = col0 >= C_QC && col0 < C_KC;
; #pragma unroll
;         for (int m = 0; m < 8; ++m) {
;           int row = brow + wr * 128 + m * 16 + fr;
;           if (ropecols && row < NL) {
;             int tpos = row & 4095;
; #pragma unroll
;             for (int pr = 0; pr < 2; ++pr) {
;               int pos = pr == 0 ? (tpos >> 6) : (tpos & 63);
; #pragma unroll
;               for (int j = 0; j < 4; ++j) {
;                 float2 cs = rope[pos * 16 + fq * 4 + j];
;                 float x1 = acc[m][2 * pr][j], x2 = acc[m][2 * pr + 1][j];
;                 acc[m][2 * pr][j] = x1 * cs.x - x2 * cs.y;
;                 acc[m][2 * pr + 1][j] = x2 * cs.x + x1 * cs.y;
	ds_read_b128 v[2:5], v0 offset:40960
	ds_read_b128 v[152:155], v0 offset:41984
	ds_read_b128 v[156:159], v0 offset:43008
	ds_read_b128 v[194:197], v0 offset:44032
	v_add_u32_e32 v0, v151, v149
	ds_read_b128 v[6:9], v0 offset:24576
	ds_read_b128 v[18:21], v0 offset:25600
	ds_read_b128 v[22:25], v0 offset:26624
	ds_read_b128 v[34:37], v0 offset:27648
	ds_read_b128 v[38:41], v0 offset:28672
	ds_read_b128 v[226:229], v0 offset:29696
	v_add_u32_e32 v50, v151, v150
	ds_read_b128 v[230:233], v0 offset:30720
	ds_read_b128 v[234:237], v50 offset:24576
	s_setprio 1
	s_waitcnt lgkmcnt(4)
	v_mfma_f32_16x16x32_bf16 v[118:121], v[2:5], v[6:9], v[126:129]
	v_mfma_f32_16x16x32_bf16 v[114:117], v[152:155], v[6:9], v[122:125]
	v_mfma_f32_16x16x32_bf16 v[126:129], v[156:159], v[6:9], v[198:201]
	v_mfma_f32_16x16x32_bf16 v[122:125], v[194:197], v[6:9], v[160:163]
	v_mfma_f32_16x16x32_bf16 v[102:105], v[2:5], v[18:21], v[110:113]
	v_mfma_f32_16x16x32_bf16 v[98:101], v[152:155], v[18:21], v[106:109]
	v_mfma_f32_16x16x32_bf16 v[110:113], v[156:159], v[18:21], v[202:205]
	v_mfma_f32_16x16x32_bf16 v[106:109], v[194:197], v[18:21], v[164:167]
	v_mfma_f32_16x16x32_bf16 v[86:89], v[2:5], v[22:25], v[94:97]
	v_mfma_f32_16x16x32_bf16 v[82:85], v[152:155], v[22:25], v[90:93]
	v_mfma_f32_16x16x32_bf16 v[94:97], v[156:159], v[22:25], v[206:209]
	v_mfma_f32_16x16x32_bf16 v[90:93], v[194:197], v[22:25], v[168:171]
	v_mfma_f32_16x16x32_bf16 v[70:73], v[2:5], v[34:37], v[78:81]
	v_mfma_f32_16x16x32_bf16 v[66:69], v[152:155], v[34:37], v[74:77]
	v_mfma_f32_16x16x32_bf16 v[78:81], v[156:159], v[34:37], v[210:213]
	v_mfma_f32_16x16x32_bf16 v[74:77], v[194:197], v[34:37], v[172:175]
	s_waitcnt lgkmcnt(0)
	v_mfma_f32_16x16x32_bf16 v[54:57], v[2:5], v[38:41], v[62:65]
	v_mfma_f32_16x16x32_bf16 v[50:53], v[152:155], v[38:41], v[58:61]
	v_mfma_f32_16x16x32_bf16 v[62:65], v[156:159], v[38:41], v[214:217]
	v_mfma_f32_16x16x32_bf16 v[58:61], v[194:197], v[38:41], v[182:185]
	v_mfma_f32_16x16x32_bf16 v[38:41], v[2:5], v[226:229], v[46:49]
	v_mfma_f32_16x16x32_bf16 v[34:37], v[152:155], v[226:229], v[42:45]
	v_mfma_f32_16x16x32_bf16 v[46:49], v[156:159], v[226:229], v[218:221]
	v_mfma_f32_16x16x32_bf16 v[42:45], v[194:197], v[226:229], v[186:189]
	v_mfma_f32_16x16x32_bf16 v[22:25], v[2:5], v[230:233], v[30:33]
	v_mfma_f32_16x16x32_bf16 v[18:21], v[152:155], v[230:233], v[26:29]
	v_mfma_f32_16x16x32_bf16 v[30:33], v[156:159], v[230:233], v[222:225]
	v_mfma_f32_16x16x32_bf16 v[26:29], v[194:197], v[230:233], v[190:193]
	v_mfma_f32_16x16x32_bf16 v[6:9], v[2:5], v[234:237], v[14:17]
	v_mfma_f32_16x16x32_bf16 v[2:5], v[152:155], v[234:237], v[10:13]
	v_mfma_f32_16x16x32_bf16 v[14:17], v[156:159], v[234:237], v[138:141]
	v_mfma_f32_16x16x32_bf16 v[10:13], v[194:197], v[234:237], v[142:145]
	s_setprio 0
	s_nop 0
	v_mov_b32_e32 v139, v146
	s_nop 0
	v_and_or_b32 v142, v139, 64, s0
	v_and_b32_e32 v153, 15, v139
	v_bfe_u32 v138, v139, 4, 2
	v_cmp_gt_i32_e32 vcc, s69, v142
	s_and_saveexec_b64 s[0:1], vcc
	s_xor_b64 s[40:41], exec, s[0:1]
	s_cbranch_execz .LBB0_231
	v_and_b32_e32 v139, 0xffffff80, v139
	v_add_u32_e32 v154, s38, v139
	v_add_u32_e32 v0, 0xfffff700, v142
	s_movk_i32 s0, 0x200
	v_or_b32_e32 v157, v154, v153
	v_cmp_gt_u32_e32 vcc, s0, v0
	v_lshlrev_b32_e32 v152, 2, v138
	v_cmp_gt_i32_e64 s[0:1], s70, v157
	s_and_b64 s[2:3], vcc, s[0:1]
	v_lshrrev_b32_e32 v138, 2, v154
	v_lshlrev_b32_e32 v139, 3, v152
	s_movk_i32 s0, 0x3e0
	v_and_or_b32 v156, v138, s0, v152
	v_lshl_or_b32 v155, v153, 7, v139
	s_and_saveexec_b64 s[0:1], s[2:3]
	s_cbranch_execz .LBB0_184
	v_lshlrev_b32_e32 v143, 3, v156
	global_load_dwordx4 v[138:141], v143, s[34:35] offset:16
	global_load_dwordx4 v[158:161], v143, s[34:35]
	s_waitcnt vmcnt(0)
	v_mul_f32_e32 v164, v116, v139
	v_mul_f32_e32 v166, v116, v138
	v_mov_b32_e32 v116, v121
	v_mov_b32_e32 v145, v160
	v_mov_b32_e32 v160, v159
	v_mul_f32_e32 v162, v120, v138
	v_mul_f32_e32 v168, v120, v139
	v_pk_mul_f32 v[138:139], v[116:117], v[140:141]
	v_mov_b32_e32 v144, v158
	v_pk_mul_f32 v[158:159], v[118:119], v[160:161]
	v_pk_mul_f32 v[160:161], v[114:115], v[160:161]
	v_mov_b32_e32 v163, v138
	v_mov_b32_e32 v165, v139
	v_pk_fma_f32 v[118:119], v[118:119], v[144:145], v[160:161] neg_lo:[0,0,1] neg_hi:[0,0,1]
	v_pk_add_f32 v[138:139], v[162:163], v[164:165] neg_lo:[0,1] neg_hi:[0,1]
	v_pk_fma_f32 v[114:115], v[114:115], v[144:145], v[158:159]
	global_load_dwordx4 v[158:161], v155, s[34:35] offset:16
	global_load_dwordx4 v[162:165], v155, s[34:35]
	v_mov_b32_e32 v120, v117
	v_pk_mul_f32 v[116:117], v[120:121], v[140:141]
	s_waitcnt vmcnt(0)
	v_mov_b32_e32 v121, v164
	v_mov_b32_e32 v164, v163
	v_mov_b32_e32 v167, v116
	v_mov_b32_e32 v169, v117
	v_mov_b32_e32 v120, v162
	v_pk_mul_f32 v[140:141], v[126:127], v[164:165]
	v_pk_mul_f32 v[144:145], v[122:123], v[164:165]
	v_mul_f32_e32 v162, v128, v158
	v_mul_f32_e32 v164, v124, v159
	v_mul_f32_e32 v158, v124, v158
	v_mov_b32_e32 v124, v129
	v_pk_add_f32 v[116:117], v[166:167], v[168:169]
	v_mul_f32_e32 v166, v128, v159
	v_pk_mul_f32 v[168:169], v[124:125], v[160:161]
	v_mov_b32_e32 v128, v125
	v_mov_b32_e32 v163, v168
	v_mov_b32_e32 v165, v169
	v_pk_mul_f32 v[124:125], v[128:129], v[160:161]
	v_pk_fma_f32 v[126:127], v[126:127], v[120:121], v[144:145] neg_lo:[0,0,1] neg_hi:[0,0,1]
	v_pk_add_f32 v[144:145], v[162:163], v[164:165] neg_lo:[0,1] neg_hi:[0,1]
	v_mov_b32_e32 v159, v124
	v_mov_b32_e32 v167, v125
	v_pk_fma_f32 v[122:123], v[122:123], v[120:121], v[140:141]
	v_pk_add_f32 v[124:125], v[158:159], v[166:167]
	v_mov_b32_e32 v128, v144
	v_mov_b32_e32 v129, v145
	v_mov_b32_e32 v120, v138
	v_mov_b32_e32 v121, v139

; template <int MODE>
; __device__ void phase_gemm(const Params& p, int l, char* smem, int mtiles, int* s_item, int wv) {
;     ...
;     auto stage = [&](int kt, int buf) {
;       char* SA = smem + buf * 24576;
;       char* SB = SA + 16384;
;       const char* ab = (const char*)A + ((size_t)brow * 1024 + kt * 32) * 2;
;       const char* bb = (const char*)Bt + ((size_t)bcol * 1024 + kt * 32) * 2;
; #pragma unroll
;       for (int i = 0; i < 4; ++i) glds16(ab + (size_t)i * (64 * 2048) + voff, SA + tid * 16 + i * 4096);
; #pragma unroll
;       for (int i = 0; i < 2; ++i) glds16(bb + (size_t)i * (64 * 2048) + voff, SB + tid * 16 + i * 4096);
;     };
;     __syncthreads();
;     stage(0, 0);
;     stage(1, 1);
;     int buf = 0;
;     for (int kt = 0; kt < 32; ++kt) {
;       if (kt < 31) asm volatile("s_waitcnt vmcnt(6)" ::: "memory");
;       else asm volatile("s_waitcnt vmcnt(0)" ::: "memory");
;       __builtin_amdgcn_s_barrier();
;       int nb = buf + 2; nb = nb >= 3 ? nb - 3 : nb;
;       if (kt + 2 < 32) stage(kt + 2, nb);
;       const char* SA = smem + buf * 24576;
;       const char* SB = SA + 16384;
;       bf16x8 af[8], bfr[4];
; #pragma unroll
;       for (int n = 0; n < 4; ++n) bfr[n] = *(const bf16x8*)(SB + (wc * 64 + n * 16 + fr) * 64 + (fq ^ (fr >> 2)) * 16);
; #pragma unroll
;       for (int m = 0; m < 8; ++m) af[m] = *(const bf16x8*)(SA + (wr * 128 + m * 16 + fr) * 64 + (fq ^ (fr >> 2)) * 16);
;       __builtin_amdgcn_sched_barrier(0);
;       __builtin_amdgcn_s_setprio(1);
; #pragma unroll
;       for (int m = 0; m < 8; ++m)
; #pragma unroll
;         for (int n = 0; n < 4; ++n) acc[m][n] = mfma16(bfr[n], af[m], acc[m][n]);
;       __builtin_amdgcn_s_setprio(0);
;       buf = buf + 1 == 3 ? 0 : buf + 1;
;     }
.LBB0_587:
	s_cmp_gt_i32 s79, 0
	s_cselect_b32 s7, -1, 2
	s_add_i32 s7, s7, s79
	s_mulk_i32 s7, 0x6000
	v_add_u32_e32 v150, s7, v141
	v_lshl_add_u64 v[146:147], v[138:139], 0, s[38:39]
	v_readfirstlane_b32 s7, v150
	v_add_u32_e32 v151, 0x1000, v150
	v_lshl_add_u64 v[148:149], v[146:147], 0, s[52:53]
	s_mov_b32 m0, s7
	v_readfirstlane_b32 s7, v151
	v_add_u32_e32 v151, 0x2000, v150
	s_waitcnt vmcnt(6)
	s_barrier
	global_load_lds_dwordx4 v[148:149], off
	v_lshl_add_u64 v[148:149], v[146:147], 0, s[54:55]
	s_mov_b32 m0, s7
	v_readfirstlane_b32 s7, v151
	global_load_lds_dwordx4 v[148:149], off
	v_lshl_add_u64 v[148:149], v[146:147], 0, s[56:57]
	s_mov_b32 m0, s7
	v_lshl_add_u64 v[146:147], v[146:147], 0, s[58:59]
	global_load_lds_dwordx4 v[148:149], off
	v_add_u32_e32 v148, 0x3000, v150
	v_add_u32_e32 v151, 0x4000, v150
	v_readfirstlane_b32 s7, v148
	s_mov_b32 m0, s7
	s_mov_b64 s[80:81], 0x1b00080
	global_load_lds_dwordx4 v[146:147], off
	v_lshl_add_u64 v[146:147], v[136:137], 0, s[38:39]
	v_readfirstlane_b32 s7, v151
	v_lshl_add_u64 v[148:149], v[146:147], 0, s[80:81]
	s_mov_b32 m0, s7
	s_mov_b64 s[80:81], 0x1b20080
	global_load_lds_dwordx4 v[148:149], off
	v_add_u32_e32 v148, 0x5000, v150
	v_lshl_add_u64 v[146:147], v[146:147], 0, s[80:81]
	v_readfirstlane_b32 s7, v148
	s_mov_b32 m0, s7
	s_mul_i32 s7, s79, 0x6000
	global_load_lds_dwordx4 v[146:147], off
	v_add_u32_e32 v174, s7, v145
	v_add_u32_e32 v158, v174, v142
	v_add_u32_e32 v175, v174, v143
	ds_read_b128 v[146:149], v158 offset:16384
	ds_read_b128 v[150:153], v158 offset:17408
	ds_read_b128 v[154:157], v158 offset:18432
	ds_read_b128 v[158:161], v158 offset:19456
	ds_read_b128 v[162:165], v175
	ds_read_b128 v[166:169], v175 offset:1024
	ds_read_b128 v[170:173], v175 offset:2048
	ds_read_b128 v[182:185], v175 offset:3072
	ds_read_b128 v[186:189], v175 offset:4096
	ds_read_b128 v[190:193], v175 offset:5120
	v_add_u32_e32 v174, v174, v144
	ds_read_b128 v[194:197], v175 offset:6144
	ds_read_b128 v[198:201], v174
	s_setprio 1
	s_waitcnt lgkmcnt(4)
	v_mfma_f32_16x16x32_bf16 v[126:129], v[146:149], v[162:165], v[126:129]
	v_mfma_f32_16x16x32_bf16 v[122:125], v[150:153], v[162:165], v[122:125]
	v_mfma_f32_16x16x32_bf16 v[118:121], v[154:157], v[162:165], v[118:121]
	v_mfma_f32_16x16x32_bf16 v[114:117], v[158:161], v[162:165], v[114:117]
	v_mfma_f32_16x16x32_bf16 v[110:113], v[146:149], v[166:169], v[110:113]
	v_mfma_f32_16x16x32_bf16 v[106:109], v[150:153], v[166:169], v[106:109]
	v_mfma_f32_16x16x32_bf16 v[102:105], v[154:157], v[166:169], v[102:105]
	v_mfma_f32_16x16x32_bf16 v[98:101], v[158:161], v[166:169], v[98:101]
	v_mfma_f32_16x16x32_bf16 v[94:97], v[146:149], v[170:173], v[94:97]
	v_mfma_f32_16x16x32_bf16 v[90:93], v[150:153], v[170:173], v[90:93]
	v_mfma_f32_16x16x32_bf16 v[86:89], v[154:157], v[170:173], v[86:89]
	v_mfma_f32_16x16x32_bf16 v[82:85], v[158:161], v[170:173], v[82:85]
	v_mfma_f32_16x16x32_bf16 v[78:81], v[146:149], v[182:185], v[78:81]
	v_mfma_f32_16x16x32_bf16 v[74:77], v[150:153], v[182:185], v[74:77]
	v_mfma_f32_16x16x32_bf16 v[70:73], v[154:157], v[182:185], v[70:73]
	v_mfma_f32_16x16x32_bf16 v[66:69], v[158:161], v[182:185], v[66:69]
	s_waitcnt lgkmcnt(0)
	v_mfma_f32_16x16x32_bf16 v[62:65], v[146:149], v[186:189], v[62:65]
	v_mfma_f32_16x16x32_bf16 v[58:61], v[150:153], v[186:189], v[58:61]
	v_mfma_f32_16x16x32_bf16 v[54:57], v[154:157], v[186:189], v[54:57]
	v_mfma_f32_16x16x32_bf16 v[50:53], v[158:161], v[186:189], v[50:53]
	v_mfma_f32_16x16x32_bf16 v[46:49], v[146:149], v[190:193], v[46:49]
	v_mfma_f32_16x16x32_bf16 v[42:45], v[150:153], v[190:193], v[42:45]
	v_mfma_f32_16x16x32_bf16 v[38:41], v[154:157], v[190:193], v[38:41]
	v_mfma_f32_16x16x32_bf16 v[34:37], v[158:161], v[190:193], v[34:37]
	v_mfma_f32_16x16x32_bf16 v[30:33], v[146:149], v[194:197], v[30:33]
	v_mfma_f32_16x16x32_bf16 v[26:29], v[150:153], v[194:197], v[26:29]
	v_mfma_f32_16x16x32_bf16 v[22:25], v[154:157], v[194:197], v[22:25]
	v_mfma_f32_16x16x32_bf16 v[18:21], v[158:161], v[194:197], v[18:21]
	v_mfma_f32_16x16x32_bf16 v[14:17], v[146:149], v[198:201], v[14:17]
	v_mfma_f32_16x16x32_bf16 v[10:13], v[150:153], v[198:201], v[10:13]
	v_mfma_f32_16x16x32_bf16 v[6:9], v[154:157], v[198:201], v[6:9]
	v_mfma_f32_16x16x32_bf16 v[2:5], v[158:161], v[198:201], v[2:5]
	s_setprio 0
	s_add_i32 s7, s79, 1
	s_cmp_lg_u32 s7, 3
	s_cselect_b32 s79, s7, 0
	s_add_u32 s38, s38, 64
	s_addc_u32 s39, s39, 0
	s_cmpk_eq_i32 s38, 0x780
	s_cbranch_scc0 .LBB0_587
	s_mul_i32 s7, s79, 0x6000
	v_add_u32_e32 v174, s7, v145
	v_add_u32_e32 v154, v174, v142
	v_add_u32_e32 v175, v174, v143
	s_waitcnt vmcnt(6)
	s_barrier
; template <int MODE>
; __device__ void phase_gemm(const Params& p, int l, char* smem, int mtiles, int* s_item, int wv) {
;     ...
;     for (int kt = 0; kt < 32; ++kt) {
;       if (kt < 31) asm volatile("s_waitcnt vmcnt(6)" ::: "memory");
;       else asm volatile("s_waitcnt vmcnt(0)" ::: "memory");
;       __builtin_amdgcn_s_barrier();
;       int nb = buf + 2; nb = nb >= 3 ? nb - 3 : nb;
;       if (kt + 2 < 32) stage(kt + 2, nb);
;       const char* SA = smem + buf * 24576;
;       const char* SB = SA + 16384;
;       bf16x8 af[8], bfr[4];
; #pragma unroll
;       for (int n = 0; n < 4; ++n) bfr[n] = *(const bf16x8*)(SB + (wc * 64 + n * 16 + fr) * 64 + (fq ^ (fr >> 2)) * 16);
; #pragma unroll
;       for (int m = 0; m < 8; ++m) af[m] = *(const bf16x8*)(SA + (wr * 128 + m * 16 + fr) * 64 + (fq ^ (fr >> 2)) * 16);
;       __builtin_amdgcn_sched_barrier(0);
;       __builtin_amdgcn_s_setprio(1);
; #pragma unroll
;       for (int m = 0; m < 8; ++m)
; #pragma unroll
;         for (int n = 0; n < 4; ++n) acc[m][n] = mfma16(bfr[n], af[m], acc[m][n]);
;       __builtin_amdgcn_s_setprio(0);
;       buf = buf + 1 == 3 ? 0 : buf + 1;
;     }
	ds_read_b128 v[136:139], v154 offset:16384
	ds_read_b128 v[146:149], v154 offset:17408
	ds_read_b128 v[150:153], v154 offset:18432
	ds_read_b128 v[154:157], v154 offset:19456
	ds_read_b128 v[158:161], v175
	ds_read_b128 v[162:165], v175 offset:1024
	ds_read_b128 v[166:169], v175 offset:2048
	ds_read_b128 v[170:173], v175 offset:3072
	ds_read_b128 v[182:185], v175 offset:4096
	ds_read_b128 v[186:189], v175 offset:5120
	v_add_u32_e32 v174, v174, v144
	ds_read_b128 v[190:193], v175 offset:6144
	ds_read_b128 v[194:197], v174
	s_setprio 1
	s_waitcnt lgkmcnt(4)
	v_mfma_f32_16x16x32_bf16 v[126:129], v[136:139], v[158:161], v[126:129]
	v_mfma_f32_16x16x32_bf16 v[122:125], v[146:149], v[158:161], v[122:125]
	v_mfma_f32_16x16x32_bf16 v[118:121], v[150:153], v[158:161], v[118:121]
	v_mfma_f32_16x16x32_bf16 v[114:117], v[154:157], v[158:161], v[114:117]
	v_mfma_f32_16x16x32_bf16 v[110:113], v[136:139], v[162:165], v[110:113]
	v_mfma_f32_16x16x32_bf16 v[106:109], v[146:149], v[162:165], v[106:109]
	v_mfma_f32_16x16x32_bf16 v[102:105], v[150:153], v[162:165], v[102:105]
	v_mfma_f32_16x16x32_bf16 v[98:101], v[154:157], v[162:165], v[98:101]
	v_mfma_f32_16x16x32_bf16 v[94:97], v[136:139], v[166:169], v[94:97]
	v_mfma_f32_16x16x32_bf16 v[90:93], v[146:149], v[166:169], v[90:93]
	v_mfma_f32_16x16x32_bf16 v[86:89], v[150:153], v[166:169], v[86:89]
	v_mfma_f32_16x16x32_bf16 v[82:85], v[154:157], v[166:169], v[82:85]
	v_mfma_f32_16x16x32_bf16 v[78:81], v[136:139], v[170:173], v[78:81]
	v_mfma_f32_16x16x32_bf16 v[74:77], v[146:149], v[170:173], v[74:77]
	v_mfma_f32_16x16x32_bf16 v[70:73], v[150:153], v[170:173], v[70:73]
	v_mfma_f32_16x16x32_bf16 v[66:69], v[154:157], v[170:173], v[66:69]
	s_waitcnt lgkmcnt(0)
	v_mfma_f32_16x16x32_bf16 v[62:65], v[136:139], v[182:185], v[62:65]
	v_mfma_f32_16x16x32_bf16 v[58:61], v[146:149], v[182:185], v[58:61]
	v_mfma_f32_16x16x32_bf16 v[54:57], v[150:153], v[182:185], v[54:57]
	v_mfma_f32_16x16x32_bf16 v[50:53], v[154:157], v[182:185], v[50:53]
	v_mfma_f32_16x16x32_bf16 v[46:49], v[136:139], v[186:189], v[46:49]
	v_mfma_f32_16x16x32_bf16 v[42:45], v[146:149], v[186:189], v[42:45]
	v_mfma_f32_16x16x32_bf16 v[38:41], v[150:153], v[186:189], v[38:41]
	v_mfma_f32_16x16x32_bf16 v[34:37], v[154:157], v[186:189], v[34:37]
	v_mfma_f32_16x16x32_bf16 v[30:33], v[136:139], v[190:193], v[30:33]
	v_mfma_f32_16x16x32_bf16 v[26:29], v[146:149], v[190:193], v[26:29]
	v_mfma_f32_16x16x32_bf16 v[22:25], v[150:153], v[190:193], v[22:25]
	v_mfma_f32_16x16x32_bf16 v[18:21], v[154:157], v[190:193], v[18:21]
	v_mfma_f32_16x16x32_bf16 v[14:17], v[136:139], v[194:197], v[14:17]
	v_mfma_f32_16x16x32_bf16 v[10:13], v[146:149], v[194:197], v[10:13]
	v_mfma_f32_16x16x32_bf16 v[6:9], v[150:153], v[194:197], v[6:9]
	v_mfma_f32_16x16x32_bf16 v[2:5], v[154:157], v[194:197], v[2:5]
	s_setprio 0
	v_add_u32_e32 v154, v145, v142
	v_add_u32_e32 v174, v145, v143
	s_waitcnt vmcnt(0)
	s_barrier
	ds_read_b128 v[136:139], v154 offset:40960
	ds_read_b128 v[146:149], v154 offset:41984
	ds_read_b128 v[150:153], v154 offset:43008
	ds_read_b128 v[154:157], v154 offset:44032
	ds_read_b128 v[158:161], v174 offset:24576
	ds_read_b128 v[162:165], v174 offset:25600
	ds_read_b128 v[166:169], v174 offset:26624
	ds_read_b128 v[170:173], v174 offset:27648
	ds_read_b128 v[182:185], v174 offset:28672
	ds_read_b128 v[186:189], v174 offset:29696
	v_add_u32_e32 v175, v145, v144
	ds_read_b128 v[190:193], v174 offset:30720
	ds_read_b128 v[194:197], v175 offset:24576
	s_setprio 1
	s_waitcnt lgkmcnt(4)
	v_mfma_f32_16x16x32_bf16 v[198:201], v[136:139], v[158:161], v[126:129]
	v_mfma_f32_16x16x32_bf16 v[122:125], v[146:149], v[158:161], v[122:125]
	v_mfma_f32_16x16x32_bf16 v[202:205], v[150:153], v[158:161], v[118:121]
	v_mfma_f32_16x16x32_bf16 v[114:117], v[154:157], v[158:161], v[114:117]
	v_mfma_f32_16x16x32_bf16 v[110:113], v[136:139], v[162:165], v[110:113]
	v_mfma_f32_16x16x32_bf16 v[106:109], v[146:149], v[162:165], v[106:109]
	v_mfma_f32_16x16x32_bf16 v[102:105], v[150:153], v[162:165], v[102:105]
	v_mfma_f32_16x16x32_bf16 v[98:101], v[154:157], v[162:165], v[98:101]
	v_mfma_f32_16x16x32_bf16 v[94:97], v[136:139], v[166:169], v[94:97]
	v_mfma_f32_16x16x32_bf16 v[90:93], v[146:149], v[166:169], v[90:93]
	v_mfma_f32_16x16x32_bf16 v[86:89], v[150:153], v[166:169], v[86:89]
	v_mfma_f32_16x16x32_bf16 v[82:85], v[154:157], v[166:169], v[82:85]
	v_mfma_f32_16x16x32_bf16 v[78:81], v[136:139], v[170:173], v[78:81]
	v_mfma_f32_16x16x32_bf16 v[74:77], v[146:149], v[170:173], v[74:77]
	v_mfma_f32_16x16x32_bf16 v[70:73], v[150:153], v[170:173], v[70:73]
	v_mfma_f32_16x16x32_bf16 v[66:69], v[154:157], v[170:173], v[66:69]
	s_waitcnt lgkmcnt(0)
; template <int MODE>
; __device__ void phase_gemm(const Params& p, int l, char* smem, int mtiles, int* s_item, int wv) {
;     ...
; #pragma unroll
;       for (int m = 0; m < 8; ++m)
; #pragma unroll
;         for (int n = 0; n < 4; ++n) acc[m][n] = mfma16(bfr[n], af[m], acc[m][n]);
;       __builtin_amdgcn_s_setprio(0);
;       buf = buf + 1 == 3 ? 0 : buf + 1;
;     }
;     ...
;       const float* xl = l == 0 ? p.x : p.out;
;       const float* xc = l == 0 ? p.ctx : (const float*)(p.ws + OFF_XC);
;       float* XC = (float*)(p.ws + OFF_XC);
;       const float* mod = (const float*)(p.ws + OFF_MOD) + (size_t)l * 17 * 3072;
; #pragma unroll
;       for (int m = 0; m < 8; ++m) {
;         int row = brow + wr * 128 + m * 16 + fr;
;         const float* xo = row < NL ? xl + (size_t)row * 1024 : xc + (size_t)(row - NL) * 1024;
;         float* xn = row < NL ? p.out + (size_t)row * 1024 : XC + (size_t)(row - NL) * 1024;
;         const float* g = mod + (row < NL ? (row >> 12) : 16) * 3072 + 2048;
; #pragma unroll
;         for (int n = 0; n < 4; ++n) {
;           int c = col0 + n * 16 + fq * 4;
;           float4 xv = *(const float4*)(xo + c);
;           float4 gv = *(const float4*)(g + c);
;           xv.x += gv.x * acc[m][n][0];
;           xv.y += gv.y * acc[m][n][1];
;           xv.z += gv.z * acc[m][n][2];
;           xv.w += gv.w * acc[m][n][3];
;           *(float4*)(xn + c) = xv;
;         }
;       }
	v_mfma_f32_16x16x32_bf16 v[62:65], v[136:139], v[182:185], v[62:65]
	v_mfma_f32_16x16x32_bf16 v[58:61], v[146:149], v[182:185], v[58:61]
	v_mfma_f32_16x16x32_bf16 v[54:57], v[150:153], v[182:185], v[54:57]
	v_mfma_f32_16x16x32_bf16 v[50:53], v[154:157], v[182:185], v[50:53]
	v_mfma_f32_16x16x32_bf16 v[46:49], v[136:139], v[186:189], v[46:49]
	v_mfma_f32_16x16x32_bf16 v[42:45], v[146:149], v[186:189], v[42:45]
	v_mfma_f32_16x16x32_bf16 v[38:41], v[150:153], v[186:189], v[38:41]
	v_mfma_f32_16x16x32_bf16 v[34:37], v[154:157], v[186:189], v[34:37]
	v_mfma_f32_16x16x32_bf16 v[30:33], v[136:139], v[190:193], v[30:33]
	v_mfma_f32_16x16x32_bf16 v[26:29], v[146:149], v[190:193], v[26:29]
	v_mfma_f32_16x16x32_bf16 v[22:25], v[150:153], v[190:193], v[22:25]
	v_mfma_f32_16x16x32_bf16 v[18:21], v[154:157], v[190:193], v[18:21]
	v_mfma_f32_16x16x32_bf16 v[14:17], v[136:139], v[194:197], v[14:17]
	v_mfma_f32_16x16x32_bf16 v[10:13], v[146:149], v[194:197], v[10:13]
	v_mfma_f32_16x16x32_bf16 v[6:9], v[150:153], v[194:197], v[6:9]
	v_mfma_f32_16x16x32_bf16 v[2:5], v[154:157], v[194:197], v[2:5]
	s_setprio 0
	v_mov_b32_e32 v118, v140
	v_mov_b32_e32 v127, s64
	v_and_b32_e32 v120, 0xffffff80, v118
	v_add_u32_e32 v120, s36, v120
	v_and_b32_e32 v119, 64, v118
	v_and_or_b32 v126, v118, 15, v120
	v_lshrrev_b32_e32 v118, 2, v118
	v_and_b32_e32 v118, 12, v118
	v_or3_b32 v156, v119, v118, s6
	v_cmp_gt_i32_e32 vcc, s70, v126
	v_add_u32_e32 v118, 0xffff0000, v126
	v_ashrrev_i32_e32 v119, 31, v126
	v_cndmask_b32_e32 v119, 0, v119, vcc
	v_cndmask_b32_e32 v118, v118, v126, vcc
	v_mov_b32_e32 v128, s50
	v_mov_b32_e32 v129, s65
	v_mov_b32_e32 v136, s51
	v_mov_b32_e32 v137, s68
	v_mov_b32_e32 v138, s31
	v_mov_b32_e32 v139, s33
	v_mov_b32_e32 v146, s30
	v_cndmask_b32_e32 v121, v127, v128, vcc
	v_cndmask_b32_e32 v120, v129, v136, vcc
	v_lshlrev_b64 v[118:119], 12, v[118:119]
	v_cndmask_b32_e32 v149, v137, v138, vcc
	v_cndmask_b32_e32 v148, v139, v146, vcc
	v_lshl_add_u64 v[120:121], v[120:121], 0, v[118:119]
	v_lshl_add_u64 v[148:149], v[148:149], 0, v[118:119]
	v_min_i32_e32 v118, 0x10000, v126
	v_ashrrev_i32_e32 v118, 12, v118
	v_mul_i32_i24_e32 v118, 0xc00, v118
	v_ashrrev_i32_e32 v119, 31, v118
	v_ashrrev_i32_e32 v157, 31, v156
	v_lshl_add_u64 v[118:119], v[118:119], 2, s[2:3]
	v_lshl_add_u64 v[158:159], v[118:119], 0, s[66:67]
	v_lshlrev_b64 v[118:119], 2, v[156:157]
	v_lshl_add_u64 v[160:161], v[120:121], 0, v[118:119]
	v_lshl_add_u64 v[120:121], v[158:159], 0, v[118:119]
	v_lshl_add_u64 v[162:163], v[148:149], 0, v[118:119]
	global_load_dwordx4 v[148:151], v[160:161], off
	global_load_dwordx4 v[152:155], v[120:121], off
	v_or_b32_e32 v120, 16, v156
	v_ashrrev_i32_e32 v121, 31, v120
	v_lshlrev_b64 v[120:121], 2, v[120:121]
	v_or_b32_e32 v147, 16, v126
	v_cmp_gt_i32_e32 vcc, s70, v147
	s_mov_b64 s[6:7], 0
	s_waitcnt vmcnt(0)
	v_pk_fma_f32 v[148:149], v[198:199], v[152:153], v[148:149]
	v_pk_fma_f32 v[150:151], v[200:201], v[154:155], v[150:151]
	global_store_dwordx4 v[162:163], v[148:151], off
	v_lshl_add_u64 v[152:153], v[158:159], 0, v[120:121]
	global_load_dwordx4 v[148:151], v[160:161], off offset:64
	s_nop 0
	global_load_dwordx4 v[152:155], v[152:153], off
	s_waitcnt vmcnt(0)
	v_pk_fma_f32 v[122:123], v[122:123], v[152:153], v[148:149]
	v_pk_fma_f32 v[124:125], v[124:125], v[154:155], v[150:151]
	global_store_dwordx4 v[162:163], v[122:125], off offset:64
	s_nop 1
	v_or_b32_e32 v122, 32, v156
	v_ashrrev_i32_e32 v123, 31, v122
	v_lshlrev_b64 v[122:123], 2, v[122:123]
	v_lshl_add_u64 v[124:125], v[158:159], 0, v[122:123]
	global_load_dwordx4 v[148:151], v[160:161], off offset:128
	global_load_dwordx4 v[152:155], v[124:125], off
	v_or_b32_e32 v124, 48, v156
	v_ashrrev_i32_e32 v125, 31, v124
	v_lshlrev_b64 v[124:125], 2, v[124:125]
	s_waitcnt vmcnt(0)
	v_pk_fma_f32 v[148:149], v[202:203], v[152:153], v[148:149]
	v_pk_fma_f32 v[150:151], v[204:205], v[154:155], v[150:151]
	global_store_dwordx4 v[162:163], v[148:151], off offset:128
	v_lshl_add_u64 v[152:153], v[158:159], 0, v[124:125]
	global_load_dwordx4 v[148:151], v[160:161], off offset:192
	s_nop 0
	global_load_dwordx4 v[152:155], v[152:153], off
	s_waitcnt vmcnt(0)
	v_pk_fma_f32 v[114:115], v[114:115], v[152:153], v[148:149]
	v_pk_fma_f32 v[116:117], v[116:117], v[154:155], v[150:151]
	global_store_dwordx4 v[162:163], v[114:117], off offset:192
	v_cndmask_b32_e32 v149, v137, v138, vcc
	v_cndmask_b32_e32 v148, v139, v146, vcc
	v_ashrrev_i32_e32 v114, 31, v147
	v_add_u32_e32 v116, 0xffff0010, v126
	v_cndmask_b32_e32 v115, 0, v114, vcc
	v_cndmask_b32_e32 v114, v116, v147, vcc
	v_min_i32_e32 v147, 0x10000, v147
	v_cndmask_b32_e32 v117, v127, v128, vcc
	v_cndmask_b32_e32 v116, v129, v136, vcc
	v_lshlrev_b64 v[114:115], 12, v[114:115]
	v_ashrrev_i32_e32 v147, 12, v147
	v_lshl_add_u64 v[116:117], v[116:117], 0, v[114:115]
	v_lshl_add_u64 v[114:115], v[148:149], 0, v[114:115]
	v_mul_i32_i24_e32 v148, 0xc00, v147
	v_ashrrev_i32_e32 v149, 31, v148
	v_lshl_add_u64 v[148:149], v[148:149], 2, s[2:3]
	v_lshl_add_u64 v[152:153], v[148:149], 0, s[66:67]
	v_lshl_add_u64 v[154:155], v[116:117], 0, v[118:119]
	v_lshl_add_u64 v[148:149], v[152:153], 0, v[118:119]
	v_lshl_add_u64 v[156:157], v[114:115], 0, v[118:119]
	global_load_dwordx4 v[114:117], v[154:155], off
	s_nop 0
	global_load_dwordx4 v[148:151], v[148:149], off
	s_waitcnt vmcnt(0)
	v_pk_fma_f32 v[110:111], v[110:111], v[148:149], v[114:115]
	v_pk_fma_f32 v[112:113], v[112:113], v[150:151], v[116:117]
	global_store_dwordx4 v[156:157], v[110:113], off
	v_lshl_add_u64 v[114:115], v[152:153], 0, v[120:121]
	global_load_dwordx4 v[110:113], v[154:155], off offset:64
	s_nop 0
	global_load_dwordx4 v[114:117], v[114:115], off
	s_waitcnt vmcnt(0)
; template <int MODE>
; __device__ void phase_gemm(const Params& p, int l, char* smem, int mtiles, int* s_item, int wv) {
;     ...
;       for (int m = 0; m < 8; ++m) {
;         int row = brow + wr * 128 + m * 16 + fr;
;         const float* xo = row < NL ? xl + (size_t)row * 1024 : xc + (size_t)(row - NL) * 1024;
;         float* xn = row < NL ? p.out + (size_t)row * 1024 : XC + (size_t)(row - NL) * 1024;
;         const float* g = mod + (row < NL ? (row >> 12) : 16) * 3072 + 2048;
; #pragma unroll
;         for (int n = 0; n < 4; ++n) {
;           int c = col0 + n * 16 + fq * 4;
;           float4 xv = *(const float4*)(xo + c);
;           float4 gv = *(const float4*)(g + c);
;           xv.x += gv.x * acc[m][n][0];
;           xv.y += gv.y * acc[m][n][1];
;           xv.z += gv.z * acc[m][n][2];
;           xv.w += gv.w * acc[m][n][3];
;           *(float4*)(xn + c) = xv;
;         }
;       }
	v_pk_fma_f32 v[106:107], v[106:107], v[114:115], v[110:111]
	v_pk_fma_f32 v[108:109], v[108:109], v[116:117], v[112:113]
	global_store_dwordx4 v[156:157], v[106:109], off offset:64
	v_lshl_add_u64 v[110:111], v[152:153], 0, v[122:123]
	global_load_dwordx4 v[106:109], v[154:155], off offset:128
	s_nop 0
	global_load_dwordx4 v[110:113], v[110:111], off
	s_waitcnt vmcnt(0)
	v_pk_fma_f32 v[102:103], v[102:103], v[110:111], v[106:107]
	v_pk_fma_f32 v[104:105], v[104:105], v[112:113], v[108:109]
	global_store_dwordx4 v[156:157], v[102:105], off offset:128
	v_lshl_add_u64 v[106:107], v[152:153], 0, v[124:125]
	global_load_dwordx4 v[102:105], v[154:155], off offset:192
	s_nop 0
	global_load_dwordx4 v[106:109], v[106:107], off
	s_waitcnt vmcnt(0)
	v_pk_fma_f32 v[98:99], v[98:99], v[106:107], v[102:103]
	v_pk_fma_f32 v[100:101], v[100:101], v[108:109], v[104:105]
	v_or_b32_e32 v104, 32, v126
	global_store_dwordx4 v[156:157], v[98:101], off offset:192
	v_cmp_gt_i32_e32 vcc, s70, v104
	s_nop 0
	v_ashrrev_i32_e32 v98, 31, v104
	v_add_u32_e32 v100, 0xffff0020, v126
	v_cndmask_b32_e32 v99, 0, v98, vcc
	v_cndmask_b32_e32 v98, v100, v104, vcc
	v_cndmask_b32_e32 v101, v127, v128, vcc
	v_cndmask_b32_e32 v100, v129, v136, vcc
	v_lshlrev_b64 v[98:99], 12, v[98:99]
	v_cndmask_b32_e32 v103, v137, v138, vcc
	v_cndmask_b32_e32 v102, v139, v146, vcc
	v_lshl_add_u64 v[100:101], v[100:101], 0, v[98:99]
	v_lshl_add_u64 v[98:99], v[102:103], 0, v[98:99]
	v_min_i32_e32 v102, 0x10000, v104
	v_ashrrev_i32_e32 v102, 12, v102
	v_mul_i32_i24_e32 v102, 0xc00, v102
	v_ashrrev_i32_e32 v103, 31, v102
	v_lshl_add_u64 v[102:103], v[102:103], 2, s[2:3]
	v_lshl_add_u64 v[106:107], v[102:103], 0, s[66:67]
	v_lshl_add_u64 v[108:109], v[100:101], 0, v[118:119]
	v_lshl_add_u64 v[102:103], v[106:107], 0, v[118:119]
	v_lshl_add_u64 v[110:111], v[98:99], 0, v[118:119]
	global_load_dwordx4 v[98:101], v[108:109], off
	s_nop 0
	global_load_dwordx4 v[102:105], v[102:103], off
	s_waitcnt vmcnt(0)
	v_pk_fma_f32 v[94:95], v[94:95], v[102:103], v[98:99]
	v_pk_fma_f32 v[96:97], v[96:97], v[104:105], v[100:101]
	global_store_dwordx4 v[110:111], v[94:97], off
	v_lshl_add_u64 v[98:99], v[106:107], 0, v[120:121]
	global_load_dwordx4 v[94:97], v[108:109], off offset:64
	s_nop 0
	global_load_dwordx4 v[98:101], v[98:99], off
	s_waitcnt vmcnt(0)
	v_pk_fma_f32 v[90:91], v[90:91], v[98:99], v[94:95]
	v_pk_fma_f32 v[92:93], v[92:93], v[100:101], v[96:97]
	global_store_dwordx4 v[110:111], v[90:93], off offset:64
	v_lshl_add_u64 v[94:95], v[106:107], 0, v[122:123]
	global_load_dwordx4 v[90:93], v[108:109], off offset:128
	s_nop 0
	global_load_dwordx4 v[94:97], v[94:95], off
	s_waitcnt vmcnt(0)
	v_pk_fma_f32 v[86:87], v[86:87], v[94:95], v[90:91]
	v_pk_fma_f32 v[88:89], v[88:89], v[96:97], v[92:93]
	global_store_dwordx4 v[110:111], v[86:89], off offset:128
	v_lshl_add_u64 v[90:91], v[106:107], 0, v[124:125]
	global_load_dwordx4 v[86:89], v[108:109], off offset:192
	s_nop 0
	global_load_dwordx4 v[90:93], v[90:91], off
	s_waitcnt vmcnt(0)
	v_pk_fma_f32 v[82:83], v[82:83], v[90:91], v[86:87]
	v_pk_fma_f32 v[84:85], v[84:85], v[92:93], v[88:89]
	v_or_b32_e32 v88, 48, v126
	global_store_dwordx4 v[110:111], v[82:85], off offset:192
	v_cmp_gt_i32_e32 vcc, s70, v88
	s_nop 0
	v_ashrrev_i32_e32 v82, 31, v88
	v_add_u32_e32 v84, 0xffff0030, v126
	v_cndmask_b32_e32 v83, 0, v82, vcc
	v_cndmask_b32_e32 v82, v84, v88, vcc
	v_cndmask_b32_e32 v85, v127, v128, vcc
	v_cndmask_b32_e32 v84, v129, v136, vcc
	v_lshlrev_b64 v[82:83], 12, v[82:83]
	v_cndmask_b32_e32 v87, v137, v138, vcc
	v_cndmask_b32_e32 v86, v139, v146, vcc
	v_lshl_add_u64 v[84:85], v[84:85], 0, v[82:83]
	v_lshl_add_u64 v[82:83], v[86:87], 0, v[82:83]
	v_min_i32_e32 v86, 0x10000, v88
	v_ashrrev_i32_e32 v86, 12, v86
	v_mul_i32_i24_e32 v86, 0xc00, v86
	v_ashrrev_i32_e32 v87, 31, v86
	v_lshl_add_u64 v[86:87], v[86:87], 2, s[2:3]
	v_lshl_add_u64 v[90:91], v[86:87], 0, s[66:67]
	v_lshl_add_u64 v[92:93], v[84:85], 0, v[118:119]
	v_lshl_add_u64 v[86:87], v[90:91], 0, v[118:119]
	v_lshl_add_u64 v[94:95], v[82:83], 0, v[118:119]
	global_load_dwordx4 v[82:85], v[92:93], off
	s_nop 0
	global_load_dwordx4 v[86:89], v[86:87], off
	s_waitcnt vmcnt(0)
	v_pk_fma_f32 v[78:79], v[78:79], v[86:87], v[82:83]
	v_pk_fma_f32 v[80:81], v[80:81], v[88:89], v[84:85]
	global_store_dwordx4 v[94:95], v[78:81], off
	v_lshl_add_u64 v[82:83], v[90:91], 0, v[120:121]
	global_load_dwordx4 v[78:81], v[92:93], off offset:64
	s_nop 0
	global_load_dwordx4 v[82:85], v[82:83], off
	s_waitcnt vmcnt(0)
	v_pk_fma_f32 v[74:75], v[74:75], v[82:83], v[78:79]
	v_pk_fma_f32 v[76:77], v[76:77], v[84:85], v[80:81]
	global_store_dwordx4 v[94:95], v[74:77], off offset:64
	v_lshl_add_u64 v[78:79], v[90:91], 0, v[122:123]
	global_load_dwordx4 v[74:77], v[92:93], off offset:128
	s_nop 0
	global_load_dwordx4 v[78:81], v[78:79], off
	s_waitcnt vmcnt(0)
	v_pk_fma_f32 v[70:71], v[70:71], v[78:79], v[74:75]
	v_pk_fma_f32 v[72:73], v[72:73], v[80:81], v[76:77]
	global_store_dwordx4 v[94:95], v[70:73], off offset:128
	v_lshl_add_u64 v[74:75], v[90:91], 0, v[124:125]
	global_load_dwordx4 v[70:73], v[92:93], off offset:192
	s_nop 0
	global_load_dwordx4 v[74:77], v[74:75], off
	s_waitcnt vmcnt(0)
; template <int MODE>
; __device__ void phase_gemm(const Params& p, int l, char* smem, int mtiles, int* s_item, int wv) {
;     ...
;       for (int m = 0; m < 8; ++m) {
;         int row = brow + wr * 128 + m * 16 + fr;
;         const float* xo = row < NL ? xl + (size_t)row * 1024 : xc + (size_t)(row - NL) * 1024;
;         float* xn = row < NL ? p.out + (size_t)row * 1024 : XC + (size_t)(row - NL) * 1024;
;         const float* g = mod + (row < NL ? (row >> 12) : 16) * 3072 + 2048;
; #pragma unroll
;         for (int n = 0; n < 4; ++n) {
;           int c = col0 + n * 16 + fq * 4;
;           float4 xv = *(const float4*)(xo + c);
;           float4 gv = *(const float4*)(g + c);
;           xv.x += gv.x * acc[m][n][0];
;           xv.y += gv.y * acc[m][n][1];
;           xv.z += gv.z * acc[m][n][2];
;           xv.w += gv.w * acc[m][n][3];
;           *(float4*)(xn + c) = xv;
;         }
;       }
	v_pk_fma_f32 v[66:67], v[66:67], v[74:75], v[70:71]
	v_pk_fma_f32 v[68:69], v[68:69], v[76:77], v[72:73]
	v_or_b32_e32 v72, 64, v126
	global_store_dwordx4 v[94:95], v[66:69], off offset:192
	v_cmp_gt_i32_e32 vcc, s70, v72
	s_nop 0
	v_ashrrev_i32_e32 v66, 31, v72
	v_add_u32_e32 v68, 0xffff0040, v126
	v_cndmask_b32_e32 v67, 0, v66, vcc
	v_cndmask_b32_e32 v66, v68, v72, vcc
	v_cndmask_b32_e32 v69, v127, v128, vcc
	v_cndmask_b32_e32 v68, v129, v136, vcc
	v_lshlrev_b64 v[66:67], 12, v[66:67]
	v_cndmask_b32_e32 v71, v137, v138, vcc
	v_cndmask_b32_e32 v70, v139, v146, vcc
	v_lshl_add_u64 v[68:69], v[68:69], 0, v[66:67]
	v_lshl_add_u64 v[66:67], v[70:71], 0, v[66:67]
	v_min_i32_e32 v70, 0x10000, v72
	v_ashrrev_i32_e32 v70, 12, v70
	v_mul_i32_i24_e32 v70, 0xc00, v70
	v_ashrrev_i32_e32 v71, 31, v70
	v_lshl_add_u64 v[70:71], v[70:71], 2, s[2:3]
	v_lshl_add_u64 v[74:75], v[70:71], 0, s[66:67]
	v_lshl_add_u64 v[76:77], v[68:69], 0, v[118:119]
	v_lshl_add_u64 v[70:71], v[74:75], 0, v[118:119]
	v_lshl_add_u64 v[78:79], v[66:67], 0, v[118:119]
	global_load_dwordx4 v[66:69], v[76:77], off
	s_nop 0
	global_load_dwordx4 v[70:73], v[70:71], off
	s_waitcnt vmcnt(0)
	v_pk_fma_f32 v[62:63], v[62:63], v[70:71], v[66:67]
	v_pk_fma_f32 v[64:65], v[64:65], v[72:73], v[68:69]
	global_store_dwordx4 v[78:79], v[62:65], off
	v_lshl_add_u64 v[66:67], v[74:75], 0, v[120:121]
	global_load_dwordx4 v[62:65], v[76:77], off offset:64
	s_nop 0
	global_load_dwordx4 v[66:69], v[66:67], off
	s_waitcnt vmcnt(0)
	v_pk_fma_f32 v[58:59], v[58:59], v[66:67], v[62:63]
	v_pk_fma_f32 v[60:61], v[60:61], v[68:69], v[64:65]
	global_store_dwordx4 v[78:79], v[58:61], off offset:64
	v_lshl_add_u64 v[62:63], v[74:75], 0, v[122:123]
	global_load_dwordx4 v[58:61], v[76:77], off offset:128
	s_nop 0
	global_load_dwordx4 v[62:65], v[62:63], off
	s_waitcnt vmcnt(0)
	v_pk_fma_f32 v[54:55], v[54:55], v[62:63], v[58:59]
	v_pk_fma_f32 v[56:57], v[56:57], v[64:65], v[60:61]
	global_store_dwordx4 v[78:79], v[54:57], off offset:128
	v_lshl_add_u64 v[58:59], v[74:75], 0, v[124:125]
	global_load_dwordx4 v[54:57], v[76:77], off offset:192
	s_nop 0
	global_load_dwordx4 v[58:61], v[58:59], off
	s_waitcnt vmcnt(0)
	v_pk_fma_f32 v[50:51], v[50:51], v[58:59], v[54:55]
	v_pk_fma_f32 v[52:53], v[52:53], v[60:61], v[56:57]
	v_or_b32_e32 v56, 0x50, v126
	global_store_dwordx4 v[78:79], v[50:53], off offset:192
	v_cmp_gt_i32_e32 vcc, s70, v56
	s_nop 0
	v_ashrrev_i32_e32 v50, 31, v56
	v_add_u32_e32 v52, 0xffff0050, v126
	v_cndmask_b32_e32 v51, 0, v50, vcc
	v_cndmask_b32_e32 v50, v52, v56, vcc
	v_cndmask_b32_e32 v53, v127, v128, vcc
	v_cndmask_b32_e32 v52, v129, v136, vcc
	v_lshlrev_b64 v[50:51], 12, v[50:51]
	v_cndmask_b32_e32 v55, v137, v138, vcc
	v_cndmask_b32_e32 v54, v139, v146, vcc
	v_lshl_add_u64 v[52:53], v[52:53], 0, v[50:51]
	v_lshl_add_u64 v[50:51], v[54:55], 0, v[50:51]
	v_min_i32_e32 v54, 0x10000, v56
	v_ashrrev_i32_e32 v54, 12, v54
	v_mul_i32_i24_e32 v54, 0xc00, v54
	v_ashrrev_i32_e32 v55, 31, v54
	v_lshl_add_u64 v[54:55], v[54:55], 2, s[2:3]
	v_lshl_add_u64 v[58:59], v[54:55], 0, s[66:67]
	v_lshl_add_u64 v[60:61], v[52:53], 0, v[118:119]
	v_lshl_add_u64 v[54:55], v[58:59], 0, v[118:119]
	v_lshl_add_u64 v[62:63], v[50:51], 0, v[118:119]
	global_load_dwordx4 v[50:53], v[60:61], off
	s_nop 0
	global_load_dwordx4 v[54:57], v[54:55], off
	s_waitcnt vmcnt(0)
	v_pk_fma_f32 v[46:47], v[46:47], v[54:55], v[50:51]
	v_pk_fma_f32 v[48:49], v[48:49], v[56:57], v[52:53]
	global_store_dwordx4 v[62:63], v[46:49], off
	v_lshl_add_u64 v[50:51], v[58:59], 0, v[120:121]
	global_load_dwordx4 v[46:49], v[60:61], off offset:64
	s_nop 0
	global_load_dwordx4 v[50:53], v[50:51], off
	s_waitcnt vmcnt(0)
	v_pk_fma_f32 v[42:43], v[42:43], v[50:51], v[46:47]
	v_pk_fma_f32 v[44:45], v[44:45], v[52:53], v[48:49]
	global_store_dwordx4 v[62:63], v[42:45], off offset:64
	v_lshl_add_u64 v[46:47], v[58:59], 0, v[122:123]
	global_load_dwordx4 v[42:45], v[60:61], off offset:128
	s_nop 0
	global_load_dwordx4 v[46:49], v[46:47], off
	s_waitcnt vmcnt(0)
	v_pk_fma_f32 v[38:39], v[38:39], v[46:47], v[42:43]
	v_pk_fma_f32 v[40:41], v[40:41], v[48:49], v[44:45]
	global_store_dwordx4 v[62:63], v[38:41], off offset:128
	v_lshl_add_u64 v[42:43], v[58:59], 0, v[124:125]
	global_load_dwordx4 v[38:41], v[60:61], off offset:192
	s_nop 0
	global_load_dwordx4 v[42:45], v[42:43], off
	s_waitcnt vmcnt(0)
; template <int MODE>
; __device__ void phase_gemm(const Params& p, int l, char* smem, int mtiles, int* s_item, int wv) {
;     ...
;       for (int m = 0; m < 8; ++m) {
;         int row = brow + wr * 128 + m * 16 + fr;
;         const float* xo = row < NL ? xl + (size_t)row * 1024 : xc + (size_t)(row - NL) * 1024;
;         float* xn = row < NL ? p.out + (size_t)row * 1024 : XC + (size_t)(row - NL) * 1024;
;         const float* g = mod + (row < NL ? (row >> 12) : 16) * 3072 + 2048;
; #pragma unroll
;         for (int n = 0; n < 4; ++n) {
;           int c = col0 + n * 16 + fq * 4;
;           float4 xv = *(const float4*)(xo + c);
;           float4 gv = *(const float4*)(g + c);
;           xv.x += gv.x * acc[m][n][0];
;           xv.y += gv.y * acc[m][n][1];
;           xv.z += gv.z * acc[m][n][2];
;           xv.w += gv.w * acc[m][n][3];
;           *(float4*)(xn + c) = xv;
;         }
;       }
	v_pk_fma_f32 v[34:35], v[34:35], v[42:43], v[38:39]
	v_pk_fma_f32 v[36:37], v[36:37], v[44:45], v[40:41]
	v_or_b32_e32 v40, 0x60, v126
	global_store_dwordx4 v[62:63], v[34:37], off offset:192
	v_cmp_gt_i32_e32 vcc, s70, v40
	s_nop 0
	v_ashrrev_i32_e32 v34, 31, v40
	v_add_u32_e32 v36, 0xffff0060, v126
	v_cndmask_b32_e32 v35, 0, v34, vcc
	v_cndmask_b32_e32 v34, v36, v40, vcc
	v_cndmask_b32_e32 v37, v127, v128, vcc
	v_cndmask_b32_e32 v36, v129, v136, vcc
	v_lshlrev_b64 v[34:35], 12, v[34:35]
	v_cndmask_b32_e32 v39, v137, v138, vcc
	v_cndmask_b32_e32 v38, v139, v146, vcc
	v_lshl_add_u64 v[36:37], v[36:37], 0, v[34:35]
	v_lshl_add_u64 v[34:35], v[38:39], 0, v[34:35]
	v_min_i32_e32 v38, 0x10000, v40
	v_ashrrev_i32_e32 v38, 12, v38
	v_mul_i32_i24_e32 v38, 0xc00, v38
	v_ashrrev_i32_e32 v39, 31, v38
	v_lshl_add_u64 v[38:39], v[38:39], 2, s[2:3]
	v_lshl_add_u64 v[42:43], v[38:39], 0, s[66:67]
	v_lshl_add_u64 v[44:45], v[36:37], 0, v[118:119]
	v_lshl_add_u64 v[38:39], v[42:43], 0, v[118:119]
	v_lshl_add_u64 v[46:47], v[34:35], 0, v[118:119]
	global_load_dwordx4 v[34:37], v[44:45], off
	s_nop 0
	global_load_dwordx4 v[38:41], v[38:39], off
	s_waitcnt vmcnt(0)
	v_pk_fma_f32 v[30:31], v[30:31], v[38:39], v[34:35]
	v_pk_fma_f32 v[32:33], v[32:33], v[40:41], v[36:37]
	global_store_dwordx4 v[46:47], v[30:33], off
	v_lshl_add_u64 v[34:35], v[42:43], 0, v[120:121]
	global_load_dwordx4 v[30:33], v[44:45], off offset:64
	s_nop 0
	global_load_dwordx4 v[34:37], v[34:35], off
	s_waitcnt vmcnt(0)
	v_pk_fma_f32 v[26:27], v[26:27], v[34:35], v[30:31]
	v_pk_fma_f32 v[28:29], v[28:29], v[36:37], v[32:33]
	global_store_dwordx4 v[46:47], v[26:29], off offset:64
	v_lshl_add_u64 v[30:31], v[42:43], 0, v[122:123]
	global_load_dwordx4 v[26:29], v[44:45], off offset:128
	s_nop 0
	global_load_dwordx4 v[30:33], v[30:31], off
	s_waitcnt vmcnt(0)
	v_pk_fma_f32 v[22:23], v[22:23], v[30:31], v[26:27]
	v_pk_fma_f32 v[24:25], v[24:25], v[32:33], v[28:29]
	global_store_dwordx4 v[46:47], v[22:25], off offset:128
	v_lshl_add_u64 v[26:27], v[42:43], 0, v[124:125]
	global_load_dwordx4 v[22:25], v[44:45], off offset:192
	s_nop 0
	global_load_dwordx4 v[26:29], v[26:27], off
	s_waitcnt vmcnt(0)
	v_pk_fma_f32 v[18:19], v[18:19], v[26:27], v[22:23]
	v_pk_fma_f32 v[20:21], v[20:21], v[28:29], v[24:25]
	v_or_b32_e32 v24, 0x70, v126
	global_store_dwordx4 v[46:47], v[18:21], off offset:192
	v_cmp_gt_i32_e32 vcc, s70, v24
	s_nop 0
	v_ashrrev_i32_e32 v18, 31, v24
	v_add_u32_e32 v20, 0xffff0070, v126
	v_cndmask_b32_e32 v19, 0, v18, vcc
	v_cndmask_b32_e32 v18, v20, v24, vcc
	v_cndmask_b32_e32 v21, v127, v128, vcc
	v_cndmask_b32_e32 v20, v129, v136, vcc
	v_lshlrev_b64 v[18:19], 12, v[18:19]
	v_cndmask_b32_e32 v23, v137, v138, vcc
	v_cndmask_b32_e32 v22, v139, v146, vcc
	v_lshl_add_u64 v[20:21], v[20:21], 0, v[18:19]
	v_lshl_add_u64 v[18:19], v[22:23], 0, v[18:19]
	v_min_i32_e32 v22, 0x10000, v24
	v_ashrrev_i32_e32 v22, 12, v22
	v_mul_i32_i24_e32 v22, 0xc00, v22
	v_ashrrev_i32_e32 v23, 31, v22
	v_lshl_add_u64 v[22:23], v[22:23], 2, s[2:3]
	v_lshl_add_u64 v[26:27], v[22:23], 0, s[66:67]
	v_lshl_add_u64 v[28:29], v[20:21], 0, v[118:119]
	v_lshl_add_u64 v[22:23], v[26:27], 0, v[118:119]
	v_lshl_add_u64 v[30:31], v[18:19], 0, v[118:119]
	global_load_dwordx4 v[18:21], v[28:29], off
	s_nop 0
	global_load_dwordx4 v[22:25], v[22:23], off
	s_waitcnt vmcnt(0)
	v_pk_fma_f32 v[14:15], v[14:15], v[22:23], v[18:19]
	v_pk_fma_f32 v[16:17], v[16:17], v[24:25], v[20:21]
	global_store_dwordx4 v[30:31], v[14:17], off
	v_lshl_add_u64 v[18:19], v[26:27], 0, v[120:121]
	global_load_dwordx4 v[14:17], v[28:29], off offset:64
	s_nop 0
	global_load_dwordx4 v[18:21], v[18:19], off
	s_waitcnt vmcnt(0)
	v_pk_fma_f32 v[10:11], v[10:11], v[18:19], v[14:15]
	v_pk_fma_f32 v[12:13], v[12:13], v[20:21], v[16:17]
	global_store_dwordx4 v[30:31], v[10:13], off offset:64
	v_lshl_add_u64 v[14:15], v[26:27], 0, v[122:123]
	global_load_dwordx4 v[10:13], v[28:29], off offset:128
	s_nop 0
	global_load_dwordx4 v[14:17], v[14:15], off
	s_waitcnt vmcnt(0)
	v_pk_fma_f32 v[6:7], v[6:7], v[14:15], v[10:11]
	v_pk_fma_f32 v[8:9], v[8:9], v[16:17], v[12:13]
	global_store_dwordx4 v[30:31], v[6:9], off offset:128
	v_lshl_add_u64 v[10:11], v[26:27], 0, v[124:125]
	global_load_dwordx4 v[6:9], v[28:29], off offset:192
	s_nop 0
	global_load_dwordx4 v[10:13], v[10:11], off
	s_waitcnt vmcnt(0)
	v_pk_fma_f32 v[2:3], v[2:3], v[10:11], v[6:7]
	v_pk_fma_f32 v[4:5], v[4:5], v[12:13], v[8:9]
	global_store_dwordx4 v[30:31], v[2:5], off offset:192
	s_branch .LBB0_580
